# v70 + straight G1 gates-tile epilogue (bias loaded once, no per-quad waited loads)
# speedup vs baseline: 1.0060x; 1.0060x over previous
.LBB1_1180:
	s_mul_i32 s15, s13, 0x4000
	s_add_i32 s15, s15, 16
	s_add_i32 s41, s13, 2
	s_cmp_ge_u32 s41, 3
	s_cselect_b32 s42, 3, 0
	s_sub_i32 s41, s41, s42
	s_mul_i32 s41, s41, 0x4000
	s_add_i32 s41, s41, 16
	s_add_i32 s41, s41, s54
	s_add_i32 s32, s14, 1
	s_min_u32 s32, s32, 15
	s_lshl_b32 s32, s32, 7
	s_add_u32 s50, s18, s32
	s_addc_u32 s51, s19, 0
	s_waitcnt vmcnt(4)
	s_barrier
	v_add_u32_e32 v202, s15, v196
	v_add_u32_e32 v203, s15, v197
	ds_read_b128 v[142:145], v198 offset:0
	ds_read_b128 v[146:149], v198 offset:2048
	ds_read_b128 v[150:153], v198 offset:4096
	ds_read_b128 v[154:157], v198 offset:6144
	ds_read_b128 v[158:161], v202
	ds_read_b128 v[216:219], v199 offset:0
	ds_read_b128 v[220:223], v199 offset:2048
	ds_read_b128 v[224:227], v199 offset:4096
	ds_read_b128 v[228:231], v199 offset:6144
	ds_read_b128 v[188:191], v203
	ds_read_b128 v[192:195], v202 offset:2048
	ds_read_b128 v[208:211], v203 offset:2048
	s_waitcnt lgkmcnt(7)
	s_add_i32 m0, s41, 0x0
	v_mfma_f32_16x16x32_bf16 v[124:127], v[142:145], v[158:161], v[124:127]
	v_mfma_f32_16x16x32_bf16 v[120:123], v[146:149], v[158:161], v[120:123]
	v_mfma_f32_16x16x32_bf16 v[116:119], v[150:153], v[158:161], v[116:119]
	v_mfma_f32_16x16x32_bf16 v[112:115], v[154:157], v[158:161], v[112:115]
	ds_read_b128 v[158:161], v202 offset:4096
	global_load_lds_dwordx4 v200, s[50:51]
	s_waitcnt lgkmcnt(3)
	s_add_i32 m0, s41, 0x400
	s_add_u32 s52, s50, 0x4000
	s_addc_u32 s53, s51, 0
	v_mfma_f32_16x16x32_bf16 v[124:127], v[216:219], v[188:191], v[124:127]
	v_mfma_f32_16x16x32_bf16 v[120:123], v[220:223], v[188:191], v[120:123]
	v_mfma_f32_16x16x32_bf16 v[116:119], v[224:227], v[188:191], v[116:119]
	v_mfma_f32_16x16x32_bf16 v[112:115], v[228:231], v[188:191], v[112:115]
	ds_read_b128 v[188:191], v203 offset:4096
	global_load_lds_dwordx4 v201, s[52:53]
	s_waitcnt lgkmcnt(3)
	s_add_i32 m0, s41, 0x800
	s_add_u32 s52, s50, 0x8000
	s_addc_u32 s53, s51, 0
	v_mfma_f32_16x16x32_bf16 v[108:111], v[142:145], v[192:195], v[108:111]
	v_mfma_f32_16x16x32_bf16 v[104:107], v[146:149], v[192:195], v[104:107]
	v_mfma_f32_16x16x32_bf16 v[100:103], v[150:153], v[192:195], v[100:103]
	v_mfma_f32_16x16x32_bf16 v[96:99], v[154:157], v[192:195], v[96:99]
	ds_read_b128 v[192:195], v202 offset:6144
	global_load_lds_dwordx4 v200, s[52:53]
	s_waitcnt lgkmcnt(3)
	s_add_i32 m0, s41, 0xc00
	s_add_u32 s52, s50, 0xc000
	s_addc_u32 s53, s51, 0
	v_mfma_f32_16x16x32_bf16 v[108:111], v[216:219], v[208:211], v[108:111]
	v_mfma_f32_16x16x32_bf16 v[104:107], v[220:223], v[208:211], v[104:107]
	v_mfma_f32_16x16x32_bf16 v[100:103], v[224:227], v[208:211], v[100:103]
	v_mfma_f32_16x16x32_bf16 v[96:99], v[228:231], v[208:211], v[96:99]
	ds_read_b128 v[208:211], v203 offset:6144
	global_load_lds_dwordx4 v201, s[52:53]
	s_waitcnt lgkmcnt(3)
	v_mfma_f32_16x16x32_bf16 v[92:95], v[142:145], v[158:161], v[92:95]
	v_mfma_f32_16x16x32_bf16 v[88:91], v[146:149], v[158:161], v[88:91]
	v_mfma_f32_16x16x32_bf16 v[84:87], v[150:153], v[158:161], v[84:87]
	v_mfma_f32_16x16x32_bf16 v[80:83], v[154:157], v[158:161], v[80:83]
	s_waitcnt lgkmcnt(2)
	v_mfma_f32_16x16x32_bf16 v[92:95], v[216:219], v[188:191], v[92:95]
	v_mfma_f32_16x16x32_bf16 v[88:91], v[220:223], v[188:191], v[88:91]
	v_mfma_f32_16x16x32_bf16 v[84:87], v[224:227], v[188:191], v[84:87]
	v_mfma_f32_16x16x32_bf16 v[80:83], v[228:231], v[188:191], v[80:83]
	s_waitcnt lgkmcnt(1)
	v_mfma_f32_16x16x32_bf16 v[76:79], v[142:145], v[192:195], v[76:79]
	v_mfma_f32_16x16x32_bf16 v[72:75], v[146:149], v[192:195], v[72:75]
	v_mfma_f32_16x16x32_bf16 v[68:71], v[150:153], v[192:195], v[68:71]
	v_mfma_f32_16x16x32_bf16 v[48:51], v[154:157], v[192:195], v[48:51]
	s_waitcnt lgkmcnt(0)
	v_mfma_f32_16x16x32_bf16 v[76:79], v[216:219], v[208:211], v[76:79]
	v_mfma_f32_16x16x32_bf16 v[72:75], v[220:223], v[208:211], v[72:75]
	v_mfma_f32_16x16x32_bf16 v[68:71], v[224:227], v[208:211], v[68:71]
	v_mfma_f32_16x16x32_bf16 v[48:51], v[228:231], v[208:211], v[48:51]
	s_add_i32 s42, s13, 1
	s_cmp_lg_u32 s13, 2
	s_cselect_b32 s13, s42, 0
	s_mul_i32 s15, s13, 0x4000
	s_add_i32 s15, s15, 16
	s_add_i32 s41, s13, 2
	s_cmp_ge_u32 s41, 3
	s_cselect_b32 s42, 3, 0
	s_sub_i32 s41, s41, s42
	s_mul_i32 s41, s41, 0x4000
	s_add_i32 s41, s41, 16
	s_add_i32 s41, s41, s54
	s_add_u32 s50, s18, s32
	s_addc_u32 s51, s19, 0
	s_add_u32 s50, s50, 0x20000
	s_addc_u32 s51, s51, 0
	s_add_u32 s46, s28, s32
	s_addc_u32 s47, s29, 0
	s_waitcnt vmcnt(4)
	s_barrier
	v_add_u32_e32 v202, s15, v196
	v_add_u32_e32 v203, s15, v197
	ds_read_b128 v[158:161], v202
	ds_read_b128 v[188:191], v203
	ds_read_b128 v[192:195], v202 offset:2048
	ds_read_b128 v[208:211], v203 offset:2048
	s_waitcnt lgkmcnt(3)
	s_add_i32 m0, s54, 0xc010
	v_mfma_f32_16x16x32_bf16 v[44:47], v[142:145], v[158:161], v[44:47]
	v_mfma_f32_16x16x32_bf16 v[40:43], v[146:149], v[158:161], v[40:43]
	v_mfma_f32_16x16x32_bf16 v[36:39], v[150:153], v[158:161], v[36:39]
	v_mfma_f32_16x16x32_bf16 v[32:35], v[154:157], v[158:161], v[32:35]
	ds_read_b128 v[158:161], v202 offset:4096
	global_load_lds_dwordx4 v200, s[46:47]
	s_waitcnt lgkmcnt(3)
	s_add_i32 m0, s54, 0xc410
	s_add_u32 s52, s46, 0x4000
	s_addc_u32 s53, s47, 0
	v_mfma_f32_16x16x32_bf16 v[44:47], v[216:219], v[188:191], v[44:47]
	v_mfma_f32_16x16x32_bf16 v[40:43], v[220:223], v[188:191], v[40:43]
	v_mfma_f32_16x16x32_bf16 v[36:39], v[224:227], v[188:191], v[36:39]
	v_mfma_f32_16x16x32_bf16 v[32:35], v[228:231], v[188:191], v[32:35]
	ds_read_b128 v[188:191], v203 offset:4096
	global_load_lds_dwordx4 v201, s[52:53]
	s_waitcnt lgkmcnt(3)
	s_add_i32 m0, s54, 0xc810
	s_add_u32 s52, s46, 0x8000
	s_addc_u32 s53, s47, 0
	v_mfma_f32_16x16x32_bf16 v[28:31], v[142:145], v[192:195], v[28:31]
	v_mfma_f32_16x16x32_bf16 v[24:27], v[146:149], v[192:195], v[24:27]
	v_mfma_f32_16x16x32_bf16 v[20:23], v[150:153], v[192:195], v[20:23]
	v_mfma_f32_16x16x32_bf16 v[16:19], v[154:157], v[192:195], v[16:19]
	ds_read_b128 v[192:195], v202 offset:6144
	global_load_lds_dwordx4 v200, s[52:53]
	s_waitcnt lgkmcnt(3)
	s_add_i32 m0, s54, 0xcc10
	s_add_u32 s52, s46, 0xc000
	s_addc_u32 s53, s47, 0
	v_mfma_f32_16x16x32_bf16 v[28:31], v[216:219], v[208:211], v[28:31]
	v_mfma_f32_16x16x32_bf16 v[24:27], v[220:223], v[208:211], v[24:27]
	v_mfma_f32_16x16x32_bf16 v[20:23], v[224:227], v[208:211], v[20:23]
	v_mfma_f32_16x16x32_bf16 v[16:19], v[228:231], v[208:211], v[16:19]
	ds_read_b128 v[208:211], v203 offset:6144
	global_load_lds_dwordx4 v201, s[52:53]
	s_waitcnt lgkmcnt(3)
	s_add_i32 m0, s41, 0x0
	v_mfma_f32_16x16x32_bf16 v[12:15], v[142:145], v[158:161], v[12:15]
	v_mfma_f32_16x16x32_bf16 v[8:11], v[146:149], v[158:161], v[8:11]
	v_mfma_f32_16x16x32_bf16 v[4:7], v[150:153], v[158:161], v[4:7]
	v_mfma_f32_16x16x32_bf16 v[0:3], v[154:157], v[158:161], v[0:3]
	global_load_lds_dwordx4 v200, s[50:51]
	s_waitcnt lgkmcnt(2)
	s_add_i32 m0, s41, 0x400
	s_add_u32 s52, s50, 0x4000
	s_addc_u32 s53, s51, 0
	v_mfma_f32_16x16x32_bf16 v[12:15], v[216:219], v[188:191], v[12:15]
	v_mfma_f32_16x16x32_bf16 v[8:11], v[220:223], v[188:191], v[8:11]
	v_mfma_f32_16x16x32_bf16 v[4:7], v[224:227], v[188:191], v[4:7]
	v_mfma_f32_16x16x32_bf16 v[0:3], v[228:231], v[188:191], v[0:3]
	global_load_lds_dwordx4 v201, s[52:53]
	s_waitcnt lgkmcnt(1)
	s_add_i32 m0, s41, 0x800
	s_add_u32 s52, s50, 0x8000
	s_addc_u32 s53, s51, 0
	v_mfma_f32_16x16x32_bf16 v[60:63], v[142:145], v[192:195], v[60:63]
	v_mfma_f32_16x16x32_bf16 v[64:67], v[146:149], v[192:195], v[64:67]
	v_mfma_f32_16x16x32_bf16 v[52:55], v[150:153], v[192:195], v[52:55]
	v_mfma_f32_16x16x32_bf16 v[56:59], v[154:157], v[192:195], v[56:59]
	global_load_lds_dwordx4 v200, s[52:53]
	s_waitcnt lgkmcnt(0)
	s_add_i32 m0, s41, 0xc00
	s_add_u32 s52, s50, 0xc000
	s_addc_u32 s53, s51, 0
	v_mfma_f32_16x16x32_bf16 v[60:63], v[216:219], v[208:211], v[60:63]
	v_mfma_f32_16x16x32_bf16 v[64:67], v[220:223], v[208:211], v[64:67]
	v_mfma_f32_16x16x32_bf16 v[52:55], v[224:227], v[208:211], v[52:55]
	v_mfma_f32_16x16x32_bf16 v[56:59], v[228:231], v[208:211], v[56:59]
	global_load_lds_dwordx4 v201, s[52:53]
	s_add_i32 s42, s13, 1
	s_cmp_lg_u32 s13, 2
	s_cselect_b32 s13, s42, 0
	s_add_i32 s14, s14, 1
	s_cmp_eq_u32 s14, 16
	s_cbranch_scc0 .LBB1_1180
	s_setprio 0
	s_waitcnt vmcnt(0)
	s_waitcnt vmcnt(0)
	s_barrier
	s_load_dwordx8 s[80:87], s[0:1], 0x180
	s_cmp_lt_i32 s4, 64
	v_readlane_b32 s12, v242, 9
	s_cselect_b64 s[10:11], -1, 0
	v_readlane_b32 s13, v242, 10
	s_and_b64 s[10:11], s[12:13], s[10:11]
	s_mov_b64 s[38:39], -1
	s_and_b64 vcc, exec, s[10:11]
	s_movk_i32 s12, 0x2020
	s_cbranch_vccnz .LBB1_1291
	v_readfirstlane_b32 s8, v162
	s_lshr_b32 s8, s8, 6
	s_and_b32 s9, s8, 1
	s_lshr_b32 s8, s8, 1
	s_cmp_eq_u32 s9, 0
	s_cbranch_scc0 .Lg1gates_done
	v_and_b32_e32 v142, 15, v168
	v_lshrrev_b32_e32 v143, 4, v168
	s_lshl_b32 s8, s8, 7
	s_add_i32 s8, s8, s6
	v_add_u32_e32 v142, s8, v142
	v_lshlrev_b32_e32 v143, 4, v143
	v_lshl_add_u32 v142, v142, 7, v143
	global_load_dwordx4 v[144:147], v143, s[22:23]
	global_load_dwordx4 v[148:151], v143, s[22:23] offset:64
	s_waitcnt vmcnt(0)
	s_mov_b32 s10, s78
	s_mov_b32 s11, s79
	v_pk_add_f32 v[124:125], v[124:125], v[144:145]
	v_pk_add_f32 v[126:127], v[126:127], v[146:147]
	v_pk_add_f32 v[120:121], v[120:121], v[148:149]
	v_pk_add_f32 v[122:123], v[122:123], v[150:151]
	s_nop 0
	global_store_dwordx4 v142, v[124:127], s[10:11] offset:0
	global_store_dwordx4 v142, v[120:123], s[10:11] offset:64
	s_add_u32 s10, s78, 0x800
	s_addc_u32 s11, s79, 0
	v_pk_add_f32 v[108:109], v[108:109], v[144:145]
	v_pk_add_f32 v[110:111], v[110:111], v[146:147]
	v_pk_add_f32 v[104:105], v[104:105], v[148:149]
	v_pk_add_f32 v[106:107], v[106:107], v[150:151]
	s_nop 0
	global_store_dwordx4 v142, v[108:111], s[10:11] offset:0
	global_store_dwordx4 v142, v[104:107], s[10:11] offset:64
	s_add_u32 s10, s78, 0x1000
	s_addc_u32 s11, s79, 0
	v_pk_add_f32 v[92:93], v[92:93], v[144:145]
	v_pk_add_f32 v[94:95], v[94:95], v[146:147]
	v_pk_add_f32 v[88:89], v[88:89], v[148:149]
	v_pk_add_f32 v[90:91], v[90:91], v[150:151]
	s_nop 0
	global_store_dwordx4 v142, v[92:95], s[10:11] offset:0
	global_store_dwordx4 v142, v[88:91], s[10:11] offset:64
	s_add_u32 s10, s78, 0x1800
	s_addc_u32 s11, s79, 0
	v_pk_add_f32 v[76:77], v[76:77], v[144:145]
	v_pk_add_f32 v[78:79], v[78:79], v[146:147]
	v_pk_add_f32 v[72:73], v[72:73], v[148:149]
	v_pk_add_f32 v[74:75], v[74:75], v[150:151]
	s_nop 0
	global_store_dwordx4 v142, v[76:79], s[10:11] offset:0
	global_store_dwordx4 v142, v[72:75], s[10:11] offset:64
	s_add_u32 s10, s78, 0x2000
	s_addc_u32 s11, s79, 0
	v_pk_add_f32 v[44:45], v[44:45], v[144:145]
	v_pk_add_f32 v[46:47], v[46:47], v[146:147]
	v_pk_add_f32 v[40:41], v[40:41], v[148:149]
	v_pk_add_f32 v[42:43], v[42:43], v[150:151]
	s_nop 0
	global_store_dwordx4 v142, v[44:47], s[10:11] offset:0
	global_store_dwordx4 v142, v[40:43], s[10:11] offset:64
	s_add_u32 s10, s78, 0x2800
	s_addc_u32 s11, s79, 0
	v_pk_add_f32 v[28:29], v[28:29], v[144:145]
	v_pk_add_f32 v[30:31], v[30:31], v[146:147]
	v_pk_add_f32 v[24:25], v[24:25], v[148:149]
	v_pk_add_f32 v[26:27], v[26:27], v[150:151]
	s_nop 0
	global_store_dwordx4 v142, v[28:31], s[10:11] offset:0
	global_store_dwordx4 v142, v[24:27], s[10:11] offset:64
	s_add_u32 s10, s78, 0x3000
	s_addc_u32 s11, s79, 0
	v_pk_add_f32 v[12:13], v[12:13], v[144:145]
	v_pk_add_f32 v[14:15], v[14:15], v[146:147]
	v_pk_add_f32 v[8:9], v[8:9], v[148:149]
	v_pk_add_f32 v[10:11], v[10:11], v[150:151]
	s_nop 0
	global_store_dwordx4 v142, v[12:15], s[10:11] offset:0
	global_store_dwordx4 v142, v[8:11], s[10:11] offset:64
	s_add_u32 s10, s78, 0x3800
	s_addc_u32 s11, s79, 0
	v_pk_add_f32 v[60:61], v[60:61], v[144:145]
	v_pk_add_f32 v[62:63], v[62:63], v[146:147]
	v_pk_add_f32 v[64:65], v[64:65], v[148:149]
	v_pk_add_f32 v[66:67], v[66:67], v[150:151]
	s_nop 0
	global_store_dwordx4 v142, v[60:63], s[10:11] offset:0
	global_store_dwordx4 v142, v[64:67], s[10:11] offset:64
.Lg1gates_done:
	s_mov_b64 s[38:39], 0
.LBB1_1291:
	s_and_b64 vcc, exec, s[38:39]
	s_cbranch_vccz .LBB1_1174
	v_mul_lo_u32 v128, v141, s3
	v_add_u32_e32 v128, 16, v128
	v_cvt_pk_bf16_f32 v124, v124, v125
	v_cvt_pk_bf16_f32 v125, v126, v127
	v_lshlrev_b32_e32 v126, 3, v140
	s_lshl_b32 s7, s7, 1
	v_add3_u32 v126, v128, v126, s7
	s_ashr_i32 s31, s30, 31
	v_cvt_pk_bf16_f32 v8, v8, v9
	v_cvt_pk_bf16_f32 v9, v10, v11
	v_add_u32_e32 v10, 0x6000, v126
	v_cvt_pk_bf16_f32 v4, v4, v5
	v_cvt_pk_bf16_f32 v5, v6, v7
	v_cvt_pk_bf16_f32 v0, v0, v1
	v_cvt_pk_bf16_f32 v1, v2, v3
	s_lshl_b64 s[8:9], s[30:31], 1
	ds_write2_b64 v10, v[4:5], v[0:1] offset0:200 offset1:204
	v_cvt_pk_bf16_f32 v0, v60, v61
	v_cvt_pk_bf16_f32 v1, v62, v63
	v_cvt_pk_bf16_f32 v2, v64, v65
	v_cvt_pk_bf16_f32 v3, v66, v67
	v_add_u32_e32 v4, 0x7000, v126
	s_add_u32 s8, s76, s8
	ds_write2_b64 v4, v[0:1], v[2:3] offset0:224 offset1:228
	v_cvt_pk_bf16_f32 v0, v52, v53
	v_cvt_pk_bf16_f32 v1, v54, v55
	v_cvt_pk_bf16_f32 v2, v56, v57
	v_cvt_pk_bf16_f32 v3, v58, v59
	v_lshlrev_b32_e32 v128, 4, v139
	s_addc_u32 s9, s77, s9
	v_cvt_pk_bf16_f32 v120, v120, v121
	v_cvt_pk_bf16_f32 v121, v122, v123
	v_cvt_pk_bf16_f32 v116, v116, v117
	v_cvt_pk_bf16_f32 v117, v118, v119
	v_cvt_pk_bf16_f32 v112, v112, v113
	v_cvt_pk_bf16_f32 v113, v114, v115
	v_cvt_pk_bf16_f32 v108, v108, v109
	v_cvt_pk_bf16_f32 v109, v110, v111
	v_cvt_pk_bf16_f32 v104, v104, v105
	v_cvt_pk_bf16_f32 v105, v106, v107
	v_add_u32_e32 v106, 0x1000, v126
	v_cvt_pk_bf16_f32 v100, v100, v101
	v_cvt_pk_bf16_f32 v101, v102, v103
	v_cvt_pk_bf16_f32 v96, v96, v97
	v_cvt_pk_bf16_f32 v97, v98, v99
	v_cvt_pk_bf16_f32 v92, v92, v93
	v_cvt_pk_bf16_f32 v93, v94, v95
	v_cvt_pk_bf16_f32 v88, v88, v89
	v_cvt_pk_bf16_f32 v89, v90, v91
	v_add_u32_e32 v90, 0x2000, v126
	v_cvt_pk_bf16_f32 v84, v84, v85
	v_cvt_pk_bf16_f32 v85, v86, v87
	v_cvt_pk_bf16_f32 v80, v80, v81
	v_cvt_pk_bf16_f32 v81, v82, v83
	v_cvt_pk_bf16_f32 v76, v76, v77
	v_cvt_pk_bf16_f32 v77, v78, v79
	v_cvt_pk_bf16_f32 v72, v72, v73
	v_cvt_pk_bf16_f32 v73, v74, v75
	v_add_u32_e32 v74, 0x3000, v126
	v_cvt_pk_bf16_f32 v68, v68, v69
	v_cvt_pk_bf16_f32 v69, v70, v71
	v_cvt_pk_bf16_f32 v48, v48, v49
	v_cvt_pk_bf16_f32 v49, v50, v51
	v_cvt_pk_bf16_f32 v44, v44, v45
	v_cvt_pk_bf16_f32 v45, v46, v47
	v_cvt_pk_bf16_f32 v40, v40, v41
	v_cvt_pk_bf16_f32 v41, v42, v43
	v_add_u32_e32 v42, 0x4000, v126
	v_cvt_pk_bf16_f32 v36, v36, v37
	v_cvt_pk_bf16_f32 v37, v38, v39
	v_cvt_pk_bf16_f32 v32, v32, v33
	v_cvt_pk_bf16_f32 v33, v34, v35
	v_cvt_pk_bf16_f32 v28, v28, v29
	v_cvt_pk_bf16_f32 v29, v30, v31
	v_cvt_pk_bf16_f32 v24, v24, v25
	v_cvt_pk_bf16_f32 v25, v26, v27
	v_add_u32_e32 v26, 0x5000, v126
	v_cvt_pk_bf16_f32 v20, v20, v21
	v_cvt_pk_bf16_f32 v21, v22, v23
	v_cvt_pk_bf16_f32 v16, v16, v17
	v_cvt_pk_bf16_f32 v17, v18, v19
	v_cvt_pk_bf16_f32 v12, v12, v13
	v_cvt_pk_bf16_f32 v13, v14, v15
	ds_write2_b64 v4, v[0:1], v[2:3] offset0:232 offset1:236
	v_add_u32_e32 v0, 16, v128
	v_lshl_add_u64 v[2:3], s[8:9], 0, v[128:129]
	s_mov_b32 s7, 0
	ds_write2_b64 v126, v[124:125], v[120:121] offset1:4
	ds_write2_b64 v126, v[116:117], v[112:113] offset0:8 offset1:12
	ds_write2_b64 v106, v[108:109], v[104:105] offset0:32 offset1:36
	ds_write2_b64 v106, v[100:101], v[96:97] offset0:40 offset1:44
	ds_write2_b64 v90, v[92:93], v[88:89] offset0:64 offset1:68
	ds_write2_b64 v90, v[84:85], v[80:81] offset0:72 offset1:76
	ds_write2_b64 v74, v[76:77], v[72:73] offset0:96 offset1:100
	ds_write2_b64 v74, v[68:69], v[48:49] offset0:104 offset1:108
	ds_write2_b64 v42, v[44:45], v[40:41] offset0:128 offset1:132
	ds_write2_b64 v42, v[36:37], v[32:33] offset0:136 offset1:140
	ds_write2_b64 v26, v[28:29], v[24:25] offset0:160 offset1:164
	ds_write2_b64 v26, v[20:21], v[16:17] offset0:168 offset1:172
	ds_write2_b64 v10, v[12:13], v[8:9] offset0:192 offset1:196
	s_waitcnt lgkmcnt(0)
	s_barrier
.LBB1_1293:
	v_add_u32_e32 v1, s7, v138
	v_ashrrev_i32_e32 v6, 4, v1
	v_mad_u64_u32 v[4:5], s[8:9], v6, s3, v[0:1]
	v_add_u32_e32 v6, s6, v6
	v_ashrrev_i32_e32 v7, 31, v6
	v_lshlrev_b64 v[6:7], 14, v[6:7]
	v_lshl_add_u64 v[8:9], v[2:3], 0, v[6:7]
	ds_read_b128 v[4:7], v4
	s_addk_i32 s7, 0x400
	s_cmpk_eq_i32 s7, 0x1000
	s_waitcnt lgkmcnt(0)
	global_store_dwordx4 v[8:9], v[4:7], off
	s_nop 1
	v_add_u32_e32 v4, 0x100, v1
	v_ashrrev_i32_e32 v6, 4, v4
	v_mad_u64_u32 v[4:5], s[8:9], v6, s3, v[0:1]
	v_add_u32_e32 v6, s6, v6
	v_ashrrev_i32_e32 v7, 31, v6
	v_lshlrev_b64 v[6:7], 14, v[6:7]
	v_lshl_add_u64 v[8:9], v[2:3], 0, v[6:7]
	ds_read_b128 v[4:7], v4
	s_waitcnt lgkmcnt(0)
	global_store_dwordx4 v[8:9], v[4:7], off
	s_nop 1
	v_add_u32_e32 v4, 0x200, v1
	v_ashrrev_i32_e32 v6, 4, v4
	v_mad_u64_u32 v[4:5], s[8:9], v6, s3, v[0:1]
	v_add_u32_e32 v6, s6, v6
	v_ashrrev_i32_e32 v7, 31, v6
	v_lshlrev_b64 v[6:7], 14, v[6:7]
	v_lshl_add_u64 v[8:9], v[2:3], 0, v[6:7]
	ds_read_b128 v[4:7], v4
	v_add_u32_e32 v1, 0x300, v1
	v_ashrrev_i32_e32 v1, 4, v1
	s_waitcnt lgkmcnt(0)
	global_store_dwordx4 v[8:9], v[4:7], off
	s_nop 1
	v_add_u32_e32 v6, s6, v1
	v_ashrrev_i32_e32 v7, 31, v6
	v_mad_u64_u32 v[4:5], s[8:9], v1, s3, v[0:1]
	v_lshlrev_b64 v[6:7], 14, v[6:7]
	v_lshl_add_u64 v[8:9], v[2:3], 0, v[6:7]
	ds_read_b128 v[4:7], v4
	s_waitcnt lgkmcnt(0)
	global_store_dwordx4 v[8:9], v[4:7], off
	s_cbranch_scc0 .LBB1_1293
	s_branch .LBB1_1174
.LBB1_1378:
	s_mov_b32 s2, 0
	s_branch .LBB1_1381
